# next-tile decode: runtime division by the group size (always 4 or 8 here) replaced by shift and mask
# baseline (speedup 1.0000x reference)
;     __host__ __device__ bool next(int i, Unit& u) const {
;         const long L = (long)i * G + c; if (L >= nwg) return false;
;         int wgid = (int)L; { const int q = nwg / NXCD, r = nwg % NXCD, xcd = wgid % NXCD, off = wgid / NXCD; wgid = (xcd < r ? xcd * (q + 1) : r * (q + 1) + (xcd - r) * q) + off; }
;         const int nig = wgm * nN, gid = wgid / nig, fm = gid * wgm, gsz = (nM - fm) < wgm ? (nM - fm) : wgm;
;         u.pm = fm + ((wgid % nig) % gsz); u.pn = (wgid % nig) / gsz; return true;
.LBB0_138:
	s_add_i32 s78, s78, 1
	s_mul_i32 s2, s78, s82
	s_mul_hi_u32 s3, s78, s85
	s_add_i32 s3, s3, s2
	s_mul_i32 s2, s78, s85
	s_add_u32 s60, s2, s16
	s_addc_u32 s61, s3, s15
	v_cmp_gt_i64_e32 vcc, s[60:61], v[140:141]
	v_cmp_lt_i64_e64 s[2:3], s[60:61], v[138:139]
	s_cbranch_vccnz .LBB0_140
	s_ashr_i32 s8, s60, 31
	s_lshr_b32 s8, s8, 29
	s_add_i32 s8, s60, s8
	s_ashr_i32 s9, s8, 3
	s_and_b32 s8, s8, -8
	s_sub_i32 s8, s60, s8
	s_cmp_lt_i32 s8, 0
	s_cselect_b32 s33, s17, 0x160
	s_mul_i32 s8, s8, s33
	s_add_i32 s8, s8, s9
	s_mul_hi_i32 s9, s8, 0x2e8ba2e9
	s_lshr_b32 s33, s9, 31
	s_ashr_i32 s9, s9, 4
	s_add_i32 s9, s9, s33
	s_lshl_b32 s33, s9, 2
	s_mulk_i32 s9, 0x58
	s_sub_i32 s8, s8, s9
	s_abs_i32 s9, s8
	s_ashr_i32 s56, s8, 2
	s_and_b32 s8, s8, 3
	s_add_i32 s58, s33, s8

;     __host__ __device__ bool next(int i, Unit& u) const {
;     ...
;         int wgid = (int)L; { const int q = nwg / NXCD, r = nwg % NXCD, xcd = wgid % NXCD, off = wgid / NXCD; wgid = (xcd < r ? xcd * (q + 1) : r * (q + 1) + (xcd - r) * q) + off; }
;         const int nig = wgm * nN, gid = wgid / nig, fm = gid * wgm, gsz = (nM - fm) < wgm ? (nM - fm) : wgm;
;         u.pm = fm + ((wgid % nig) % gsz); u.pn = (wgid % nig) / gsz; return true;
.LBB0_220:
	s_ashr_i32 s4, s62, 3
	s_add_i32 s4, s73, s4
	s_ashr_i32 s5, s4, 31
	s_lshr_b32 s5, s5, 27
	s_add_i32 s5, s4, s5
	s_ashr_i32 s8, s5, 5
	s_lshl_b32 s8, s8, 3
	s_andn2_b32 s5, s5, 31
	s_sub_i32 s4, s4, s5
	s_abs_i32 s5, s4
	s_ashr_i32 s93, s4, 3
	s_and_b32 s4, s4, 7
	s_add_i32 s94, s8, s4

;     __host__ __device__ bool next(int i, Unit& u) const {
;     ...
;         int wgid = (int)L; { const int q = nwg / NXCD, r = nwg % NXCD, xcd = wgid % NXCD, off = wgid / NXCD; wgid = (xcd < r ? xcd * (q + 1) : r * (q + 1) + (xcd - r) * q) + off; }
;         const int nig = wgm * nN, gid = wgid / nig, fm = gid * wgm, gsz = (nM - fm) < wgm ? (nM - fm) : wgm;
;         u.pm = fm + ((wgid % nig) % gsz); u.pn = (wgid % nig) / gsz; return true;
.LBB0_312:
	s_add_i32 s96, s96, 1
	s_mul_i32 s2, s96, s97
	s_mul_hi_u32 s3, s96, s82
	s_add_i32 s3, s3, s2
	s_mul_i32 s2, s96, s82
	s_add_u32 s68, s2, s16
	s_addc_u32 s69, s3, s17
	v_cmp_gt_i64_e32 vcc, s[68:69], v[138:139]
	v_cmp_lt_i64_e64 s[2:3], s[68:69], v[136:137]
	s_cbranch_vccnz .LBB0_314
	s_ashr_i32 s7, s68, 31
	s_lshr_b32 s7, s7, 29
	s_add_i32 s7, s68, s7
	s_ashr_i32 s8, s7, 3
	s_and_b32 s7, s7, -8
	s_sub_i32 s7, s68, s7
	s_cmp_lt_i32 s7, 0
	s_movk_i32 s9, 0xf1
	s_cselect_b32 s9, s9, 0xf0
	s_mul_i32 s7, s7, s9
	s_add_i32 s7, s7, s8
	s_mul_hi_i32 s8, s7, 0x88888889
	s_add_i32 s8, s8, s7
	s_lshr_b32 s9, s8, 31
	s_ashr_i32 s8, s8, 5
	s_add_i32 s8, s8, s9
	s_lshl_b32 s9, s8, 2
	s_mul_i32 s8, s8, 60
	s_sub_i32 s7, s7, s8
	s_abs_i32 s8, s7
	s_ashr_i32 s60, s7, 2
	s_and_b32 s7, s7, 3
	s_add_i32 s62, s9, s7

;     __host__ __device__ bool next(int i, Unit& u) const {
;     ...
;         int wgid = (int)L; { const int q = nwg / NXCD, r = nwg % NXCD, xcd = wgid % NXCD, off = wgid / NXCD; wgid = (xcd < r ? xcd * (q + 1) : r * (q + 1) + (xcd - r) * q) + off; }
;         const int nig = wgm * nN, gid = wgid / nig, fm = gid * wgm, gsz = (nM - fm) < wgm ? (nM - fm) : wgm;
;         u.pm = fm + ((wgid % nig) % gsz); u.pn = (wgid % nig) / gsz; return true;
.LBB0_642:
	s_ashr_i32 s2, s60, 3
	s_add_i32 s2, s62, s2
	s_ashr_i32 s3, s2, 31
	s_lshr_b32 s3, s3, 27
	s_add_i32 s3, s2, s3
	s_ashr_i32 s8, s3, 5
	s_lshl_b32 s8, s8, 3
	s_andn2_b32 s3, s3, 31
	s_sub_i32 s2, s2, s3
	s_abs_i32 s3, s2
	s_ashr_i32 s60, s2, 3
	s_and_b32 s2, s2, 7
	s_add_i32 s87, s8, s2

;     __host__ __device__ bool next(int i, Unit& u) const {
;     ...
;         int wgid = (int)L; { const int q = nwg / NXCD, r = nwg % NXCD, xcd = wgid % NXCD, off = wgid / NXCD; wgid = (xcd < r ? xcd * (q + 1) : r * (q + 1) + (xcd - r) * q) + off; }
;         const int nig = wgm * nN, gid = wgid / nig, fm = gid * wgm, gsz = (nM - fm) < wgm ? (nM - fm) : wgm;
;         u.pm = fm + ((wgid % nig) % gsz); u.pn = (wgid % nig) / gsz; return true;
.LBB0_668:
	s_ashr_i32 s8, s56, 3
	s_add_i32 s8, s58, s8
	s_ashr_i32 s9, s8, 31
	s_lshr_b32 s9, s9, 27
	s_add_i32 s9, s8, s9
	s_ashr_i32 s54, s9, 5
	s_lshl_b32 s55, s54, 3
	s_andn2_b32 s9, s9, 31
	s_sub_i32 s8, s8, s9
	s_abs_i32 s9, s8
	s_ashr_i32 s54, s8, 3
	s_and_b32 s8, s8, 7
	s_add_i32 s56, s55, s8

;     __host__ __device__ bool next(int i, Unit& u) const {
;     ...
;         int wgid = (int)L; { const int q = nwg / NXCD, r = nwg % NXCD, xcd = wgid % NXCD, off = wgid / NXCD; wgid = (xcd < r ? xcd * (q + 1) : r * (q + 1) + (xcd - r) * q) + off; }
;         const int nig = wgm * nN, gid = wgid / nig, fm = gid * wgm, gsz = (nM - fm) < wgm ? (nM - fm) : wgm;
;         u.pm = fm + ((wgid % nig) % gsz); u.pn = (wgid % nig) / gsz; return true;
.LBB0_749:
	s_ashr_i32 s56, s58, 3
	s_add_i32 s56, s60, s56
	s_ashr_i32 s57, s56, 31
	s_lshr_b32 s57, s57, 27
	s_add_i32 s57, s56, s57
	s_ashr_i32 s58, s57, 5
	s_lshl_b32 s58, s58, 3
	s_andn2_b32 s57, s57, 31
	s_sub_i32 s57, s56, s57
	s_abs_i32 s56, s57
	s_ashr_i32 s56, s57, 3
	s_and_b32 s57, s57, 7
	s_add_i32 s58, s58, s57

;     __host__ __device__ bool next(int i, Unit& u) const {
;     ...
;         int wgid = (int)L; { const int q = nwg / NXCD, r = nwg % NXCD, xcd = wgid % NXCD, off = wgid / NXCD; wgid = (xcd < r ? xcd * (q + 1) : r * (q + 1) + (xcd - r) * q) + off; }
;         const int nig = wgm * nN, gid = wgid / nig, fm = gid * wgm, gsz = (nM - fm) < wgm ? (nM - fm) : wgm;
;         u.pm = fm + ((wgid % nig) % gsz); u.pn = (wgid % nig) / gsz; return true;
.LBB0_835:
	s_add_i32 s70, s70, 1
	s_mul_i32 s2, s70, s72
	s_mul_hi_u32 s3, s70, s73
	s_add_i32 s3, s3, s2
	s_mul_i32 s2, s70, s73
	s_add_u32 s56, s2, s16
	s_addc_u32 s57, s3, s15
	v_cmp_gt_i64_e32 vcc, s[56:57], v[138:139]
	v_cmp_lt_i64_e64 s[2:3], s[56:57], v[136:137]
	s_cbranch_vccnz .LBB0_837
	s_ashr_i32 s52, s56, 31
	s_lshr_b32 s52, s52, 29
	s_add_i32 s52, s56, s52
	s_ashr_i32 s53, s52, 3
	s_and_b32 s52, s52, -8
	s_sub_i32 s52, s56, s52
	s_cmp_lt_i32 s52, 0
	s_cselect_b32 s54, s17, 0x160
	s_mul_i32 s52, s52, s54
	s_add_i32 s52, s52, s53
	s_mul_hi_i32 s53, s52, 0x2e8ba2e9
	s_lshr_b32 s54, s53, 31
	s_ashr_i32 s53, s53, 4
	s_add_i32 s53, s53, s54
	s_lshl_b32 s54, s53, 2
	s_mulk_i32 s53, 0x58
	s_sub_i32 s53, s52, s53
	s_abs_i32 s52, s53
	s_ashr_i32 s52, s53, 2
	s_and_b32 s53, s53, 3
	s_add_i32 s54, s54, s53

;     __host__ __device__ bool next(int i, Unit& u) const {
;     ...
;         int wgid = (int)L; { const int q = nwg / NXCD, r = nwg % NXCD, xcd = wgid % NXCD, off = wgid / NXCD; wgid = (xcd < r ? xcd * (q + 1) : r * (q + 1) + (xcd - r) * q) + off; }
;         const int nig = wgm * nN, gid = wgid / nig, fm = gid * wgm, gsz = (nM - fm) < wgm ? (nM - fm) : wgm;
;         u.pm = fm + ((wgid % nig) % gsz); u.pn = (wgid % nig) / gsz; return true;
.LBB0_918:
	s_ashr_i32 s4, s62, 3
	s_add_i32 s4, s66, s4
	s_ashr_i32 s5, s4, 31
	s_lshr_b32 s5, s5, 27
	s_add_i32 s5, s4, s5
	s_ashr_i32 s33, s5, 5
	s_lshl_b32 s33, s33, 3
	s_andn2_b32 s5, s5, 31
	s_sub_i32 s4, s4, s5
	s_abs_i32 s5, s4
	s_ashr_i32 s85, s4, 3
	s_and_b32 s4, s4, 7
	s_add_i32 s86, s33, s4
